# write-through (sc1) also on the late weight conversion stores and the scan output stores
# baseline (speedup 1.0000x reference)
.Lscan_loop:
	v_readlane_b32 s56, v57, s3
	v_cvt_pk_bf16_f32 v144, v0, v1
	v_cvt_pk_bf16_f32 v145, v2, v3
	v_cvt_pk_bf16_f32 v146, v4, v5
	v_cvt_pk_bf16_f32 v147, v6, v7
	v_cvt_pk_bf16_f32 v148, v8, v9
	v_cvt_pk_bf16_f32 v149, v10, v11
	v_cvt_pk_bf16_f32 v150, v12, v13
	v_cvt_pk_bf16_f32 v151, v14, v15
	s_waitcnt lgkmcnt(7)
	v_mfma_f32_16x16x32_bf16 v[64:67], v[96:99], v[144:147], 0
	ds_read_b128 v[96:99], v93 offset:12288
	v_cvt_pk_bf16_f32 v152, v16, v17
	v_cvt_pk_bf16_f32 v153, v18, v19
	v_cvt_pk_bf16_f32 v154, v20, v21
	v_cvt_pk_bf16_f32 v155, v22, v23
	s_waitcnt lgkmcnt(7)
	v_mfma_f32_16x16x32_bf16 v[64:67], v[100:103], v[148:151], v[64:67]
	ds_read_b128 v[100:103], v93 offset:13312
	v_cvt_pk_bf16_f32 v156, v28, v29
	v_cvt_pk_bf16_f32 v157, v30, v31
	v_cvt_pk_bf16_f32 v158, v24, v25
	v_cvt_pk_bf16_f32 v159, v26, v27
	s_waitcnt lgkmcnt(7)
	v_mfma_f32_16x16x32_bf16 v[64:67], v[104:107], v[152:155], v[64:67]
	ds_read_b128 v[104:107], v93 offset:14336
	v_mul_f32_e32 v0, s56, v0
	v_mul_f32_e32 v1, s56, v1
	s_waitcnt lgkmcnt(7)
	v_mfma_f32_16x16x32_bf16 v[64:67], v[108:111], v[156:159], v[64:67]
	ds_read_b128 v[108:111], v93 offset:15360
	v_mul_f32_e32 v2, s56, v2
	v_mul_f32_e32 v3, s56, v3
	s_waitcnt lgkmcnt(7)
	v_mfma_f32_16x16x32_bf16 v[68:71], v[112:115], v[144:147], 0
	ds_read_b128 v[112:115], v93 offset:16384
	v_mul_f32_e32 v4, s56, v4
	v_mul_f32_e32 v5, s56, v5
	s_waitcnt lgkmcnt(7)
	v_mfma_f32_16x16x32_bf16 v[68:71], v[116:119], v[148:151], v[68:71]
	ds_read_b128 v[116:119], v93 offset:17408
	v_mul_f32_e32 v6, s56, v6
	v_mul_f32_e32 v7, s56, v7
	v_mfma_f32_16x16x32_bf16 v[68:71], v[120:123], v[152:155], v[68:71]
	ds_read_b128 v[120:123], v93 offset:18432
	v_mul_f32_e32 v8, s56, v8
	v_mul_f32_e32 v9, s56, v9
	v_mfma_f32_16x16x32_bf16 v[68:71], v[124:127], v[156:159], v[68:71]
	ds_read_b128 v[124:127], v93 offset:19456
	v_mul_f32_e32 v10, s56, v10
	v_mul_f32_e32 v11, s56, v11
	v_mfma_f32_16x16x32_bf16 v[72:75], v[128:131], v[144:147], 0
	ds_read_b128 v[128:131], v93 offset:20480
	v_mul_f32_e32 v12, s56, v12
	v_mul_f32_e32 v13, s56, v13
	v_mfma_f32_16x16x32_bf16 v[72:75], v[132:135], v[148:151], v[72:75]
	ds_read_b128 v[132:135], v93 offset:21504
	v_mul_f32_e32 v14, s56, v14
	v_mul_f32_e32 v15, s56, v15
	v_mfma_f32_16x16x32_bf16 v[72:75], v[136:139], v[152:155], v[72:75]
	ds_read_b128 v[136:139], v93 offset:22528
	v_mul_f32_e32 v16, s56, v16
	v_mul_f32_e32 v17, s56, v17
	v_mfma_f32_16x16x32_bf16 v[72:75], v[140:143], v[156:159], v[72:75]
	ds_read_b128 v[140:143], v93 offset:23552
	v_mul_f32_e32 v18, s56, v18
	v_mul_f32_e32 v19, s56, v19
	s_waitcnt lgkmcnt(11)
	v_mfma_f32_16x16x32_bf16 v[76:79], v[96:99], v[144:147], 0
	ds_read_b128 v[96:99], v93 offset:24576
	v_lshlrev_b32_e32 v88, 16, v172
	v_and_b32_e32 v89, 0xffff0000, v172
	v_sub_f32_e32 v64, v88, v64
	v_sub_f32_e32 v65, v89, v65
	s_waitcnt lgkmcnt(11)
	v_mfma_f32_16x16x32_bf16 v[76:79], v[100:103], v[148:151], v[76:79]
	ds_read_b128 v[100:103], v93 offset:25600
	v_lshlrev_b32_e32 v88, 16, v173
	v_and_b32_e32 v89, 0xffff0000, v173
	v_sub_f32_e32 v66, v88, v66
	v_sub_f32_e32 v67, v89, v67
	s_waitcnt lgkmcnt(11)
	v_mfma_f32_16x16x32_bf16 v[76:79], v[104:107], v[152:155], v[76:79]
	ds_read_b128 v[104:107], v93 offset:26624
	v_lshlrev_b32_e32 v88, 16, v174
	v_and_b32_e32 v89, 0xffff0000, v174
	v_sub_f32_e32 v68, v88, v68
	v_sub_f32_e32 v69, v89, v69
	s_waitcnt lgkmcnt(11)
	v_mfma_f32_16x16x32_bf16 v[76:79], v[108:111], v[156:159], v[76:79]
	ds_read_b128 v[108:111], v93 offset:27648
	v_lshlrev_b32_e32 v88, 16, v175
	v_and_b32_e32 v89, 0xffff0000, v175
	v_sub_f32_e32 v70, v88, v70
	v_sub_f32_e32 v71, v89, v71
	s_waitcnt lgkmcnt(11)
	v_mfma_f32_16x16x32_bf16 v[32:35], v[112:115], v[144:147], 0
	ds_read_b128 v[112:115], v93 offset:28672
	v_cvt_pk_bf16_f32 v80, v64, v65
	v_cvt_pk_bf16_f32 v81, v66, v67
	v_cvt_pk_bf16_f32 v82, v68, v69
	v_cvt_pk_bf16_f32 v83, v70, v71
	s_waitcnt lgkmcnt(11)
	v_mfma_f32_16x16x32_bf16 v[32:35], v[116:119], v[148:151], v[32:35]
	ds_read_b128 v[116:119], v93 offset:29696
	v_lshlrev_b32_e32 v88, 16, v176
	v_and_b32_e32 v89, 0xffff0000, v176
	v_sub_f32_e32 v72, v88, v72
	v_sub_f32_e32 v73, v89, v73
	s_waitcnt lgkmcnt(11)
	v_mfma_f32_16x16x32_bf16 v[32:35], v[120:123], v[152:155], v[32:35]
	ds_read_b128 v[120:123], v93 offset:30720
	v_lshlrev_b32_e32 v88, 16, v177
	v_and_b32_e32 v89, 0xffff0000, v177
	v_sub_f32_e32 v74, v88, v74
	v_sub_f32_e32 v75, v89, v75
	s_waitcnt lgkmcnt(11)
	v_mfma_f32_16x16x32_bf16 v[32:35], v[124:127], v[156:159], v[32:35]
	ds_read_b128 v[124:127], v93 offset:31744
	v_lshlrev_b32_e32 v88, 16, v178
	v_and_b32_e32 v89, 0xffff0000, v178
	v_sub_f32_e32 v76, v88, v76
	v_sub_f32_e32 v77, v89, v77
	s_waitcnt lgkmcnt(11)
	v_mfma_f32_16x16x32_bf16 v[36:39], v[128:131], v[144:147], 0
	ds_read_b128 v[128:131], v93 offset:32768
	v_lshlrev_b32_e32 v88, 16, v179
	v_and_b32_e32 v89, 0xffff0000, v179
	v_sub_f32_e32 v78, v88, v78
	v_sub_f32_e32 v79, v89, v79
	s_waitcnt lgkmcnt(11)
	v_mfma_f32_16x16x32_bf16 v[36:39], v[132:135], v[148:151], v[36:39]
	ds_read_b128 v[132:135], v93 offset:34816
	v_cvt_pk_bf16_f32 v84, v72, v73
	v_cvt_pk_bf16_f32 v85, v74, v75
	v_cvt_pk_bf16_f32 v86, v76, v77
	v_cvt_pk_bf16_f32 v87, v78, v79
	s_waitcnt lgkmcnt(11)
	v_mfma_f32_16x16x32_bf16 v[36:39], v[136:139], v[152:155], v[36:39]
	ds_read_b128 v[136:139], v93 offset:36864
	v_mul_f32_e32 v20, s56, v20
	s_waitcnt lgkmcnt(11)
	v_mfma_f32_16x16x32_bf16 v[36:39], v[140:143], v[156:159], v[36:39]
	ds_read_b128 v[140:143], v93 offset:37888
	v_mul_f32_e32 v21, s56, v21
	s_waitcnt lgkmcnt(11)
	v_mfma_f32_16x16x32_bf16 v[40:43], v[96:99], v[144:147], 0
	ds_read_b128 v[96:99], v93 offset:38912
	v_mul_f32_e32 v22, s56, v22
	s_waitcnt lgkmcnt(11)
	v_mfma_f32_16x16x32_bf16 v[40:43], v[100:103], v[148:151], v[40:43]
	ds_read_b128 v[100:103], v93 offset:39936
	v_mul_f32_e32 v23, s56, v23
	s_waitcnt lgkmcnt(11)
	v_mfma_f32_16x16x32_bf16 v[40:43], v[104:107], v[152:155], v[40:43]
	ds_read_b128 v[104:107], v93 offset:40960
	v_mul_f32_e32 v24, s56, v24
	s_waitcnt lgkmcnt(11)
	v_mfma_f32_16x16x32_bf16 v[40:43], v[108:111], v[156:159], v[40:43]
	ds_read_b128 v[108:111], v93 offset:41984
	v_mul_f32_e32 v25, s56, v25
	s_waitcnt lgkmcnt(11)
	v_mfma_f32_16x16x32_bf16 v[44:47], v[112:115], v[144:147], 0
	ds_read_b128 v[112:115], v93 offset:43008
	v_mul_f32_e32 v26, s56, v26
	s_waitcnt lgkmcnt(11)
	v_mfma_f32_16x16x32_bf16 v[44:47], v[116:119], v[148:151], v[44:47]
	ds_read_b128 v[116:119], v93 offset:44032
	v_mul_f32_e32 v27, s56, v27
	s_waitcnt lgkmcnt(11)
	v_mfma_f32_16x16x32_bf16 v[44:47], v[120:123], v[152:155], v[44:47]
	ds_read_b128 v[120:123], v93 offset:45056
	v_mul_f32_e32 v28, s56, v28
	s_waitcnt lgkmcnt(11)
	v_mfma_f32_16x16x32_bf16 v[44:47], v[124:127], v[156:159], v[44:47]
	ds_read_b128 v[124:127], v93 offset:46080
	v_mul_f32_e32 v29, s56, v29
	s_waitcnt lgkmcnt(11)
	v_mfma_f32_16x16x32_bf16 v[32:35], v[128:131], v[80:83], v[32:35]
	ds_read_b128 v[128:131], v93 offset:47104
	v_mul_f32_e32 v30, s56, v30
	s_waitcnt lgkmcnt(11)
	v_mfma_f32_16x16x32_bf16 v[36:39], v[132:135], v[80:83], v[36:39]
	ds_read_b128 v[132:135], v93 offset:48128
	v_mul_f32_e32 v31, s56, v31
	s_waitcnt lgkmcnt(11)
	v_mfma_f32_16x16x32_bf16 v[40:43], v[136:139], v[80:83], v[40:43]
	ds_read_b128 v[136:139], v93 offset:49152
	s_waitcnt lgkmcnt(11)
	v_mfma_f32_16x16x32_bf16 v[40:43], v[140:143], v[84:87], v[40:43]
	ds_read_b128 v[140:143], v93 offset:50176
	s_waitcnt lgkmcnt(11)
	v_mfma_f32_16x16x32_bf16 v[44:47], v[96:99], v[80:83], v[44:47]
	ds_read_b128 v[96:99], v93 offset:51200
	s_waitcnt lgkmcnt(11)
	v_mfma_f32_16x16x32_bf16 v[44:47], v[100:103], v[84:87], v[44:47]
	ds_read_b128 v[100:103], v93 offset:52224
	s_waitcnt lgkmcnt(11)
	v_mfma_f32_16x16x32_bf16 v[0:3], v[104:107], v[80:83], v[0:3]
	ds_read_b128 v[104:107], v93 offset:53248
	s_waitcnt lgkmcnt(11)
	v_mfma_f32_16x16x32_bf16 v[0:3], v[108:111], v[84:87], v[0:3]
	ds_read_b128 v[108:111], v93 offset:54272
	s_waitcnt lgkmcnt(11)
	v_mfma_f32_16x16x32_bf16 v[4:7], v[112:115], v[80:83], v[4:7]
	ds_read_b128 v[112:115], v93 offset:55296
	s_mov_b64 vcc, s[16:17]
	v_cndmask_b32_dpp v200, v33, v32, vcc quad_perm:[1,0,3,2] row_mask:0xf bank_mask:0xf
	v_cndmask_b32_dpp v202, v35, v34, vcc quad_perm:[1,0,3,2] row_mask:0xf bank_mask:0xf
	v_cndmask_b32_dpp v204, v37, v36, vcc quad_perm:[1,0,3,2] row_mask:0xf bank_mask:0xf
	v_cndmask_b32_dpp v206, v39, v38, vcc quad_perm:[1,0,3,2] row_mask:0xf bank_mask:0xf
	s_waitcnt lgkmcnt(11)
	v_mfma_f32_16x16x32_bf16 v[4:7], v[116:119], v[84:87], v[4:7]
	ds_read_b128 v[116:119], v93 offset:56320
	s_mov_b64 vcc, s[18:19]
	v_cndmask_b32_dpp v201, v32, v33, vcc quad_perm:[1,0,3,2] row_mask:0xf bank_mask:0xf
	v_cndmask_b32_dpp v203, v34, v35, vcc quad_perm:[1,0,3,2] row_mask:0xf bank_mask:0xf
	v_cndmask_b32_dpp v205, v36, v37, vcc quad_perm:[1,0,3,2] row_mask:0xf bank_mask:0xf
	v_cndmask_b32_dpp v207, v38, v39, vcc quad_perm:[1,0,3,2] row_mask:0xf bank_mask:0xf
	s_waitcnt lgkmcnt(11)
	v_mfma_f32_16x16x32_bf16 v[8:11], v[120:123], v[80:83], v[8:11]
	s_mov_b64 vcc, s[20:21]
	v_cndmask_b32_dpp v52, v202, v200, vcc quad_perm:[2,3,0,1] row_mask:0xf bank_mask:0xf
	v_cndmask_b32_dpp v53, v203, v201, vcc quad_perm:[2,3,0,1] row_mask:0xf bank_mask:0xf
	v_cndmask_b32_dpp v58, v206, v204, vcc quad_perm:[2,3,0,1] row_mask:0xf bank_mask:0xf
	v_cndmask_b32_dpp v59, v207, v205, vcc quad_perm:[2,3,0,1] row_mask:0xf bank_mask:0xf
	v_add_u32_e32 v93, s8, v93
	v_add_u32_e32 v94, s8, v94
	s_sub_i32 s8, 0, s8
	s_waitcnt lgkmcnt(10)
	v_mfma_f32_16x16x32_bf16 v[8:11], v[124:127], v[84:87], v[8:11]
	s_mov_b64 vcc, s[22:23]
	v_cndmask_b32_dpp v54, v200, v202, vcc quad_perm:[2,3,0,1] row_mask:0xf bank_mask:0xf
	v_cndmask_b32_dpp v55, v201, v203, vcc quad_perm:[2,3,0,1] row_mask:0xf bank_mask:0xf
	v_cndmask_b32_dpp v60, v204, v206, vcc quad_perm:[2,3,0,1] row_mask:0xf bank_mask:0xf
	v_cndmask_b32_dpp v61, v205, v207, vcc quad_perm:[2,3,0,1] row_mask:0xf bank_mask:0xf
	s_waitcnt lgkmcnt(9)
	v_mfma_f32_16x16x32_bf16 v[12:15], v[128:131], v[80:83], v[12:15]
	global_store_dwordx4 v190, v[52:55], s[14:15] sc1
	global_store_dwordx4 v191, v[58:61], s[14:15] sc1
	s_mov_b64 vcc, s[16:17]
	v_cndmask_b32_dpp v208, v41, v40, vcc quad_perm:[1,0,3,2] row_mask:0xf bank_mask:0xf
	v_cndmask_b32_dpp v210, v43, v42, vcc quad_perm:[1,0,3,2] row_mask:0xf bank_mask:0xf
	v_cndmask_b32_dpp v212, v45, v44, vcc quad_perm:[1,0,3,2] row_mask:0xf bank_mask:0xf
	v_cndmask_b32_dpp v214, v47, v46, vcc quad_perm:[1,0,3,2] row_mask:0xf bank_mask:0xf
	s_waitcnt lgkmcnt(8)
	v_mfma_f32_16x16x32_bf16 v[12:15], v[132:135], v[84:87], v[12:15]
	s_mov_b64 vcc, s[18:19]
	v_cndmask_b32_dpp v209, v40, v41, vcc quad_perm:[1,0,3,2] row_mask:0xf bank_mask:0xf
	v_cndmask_b32_dpp v211, v42, v43, vcc quad_perm:[1,0,3,2] row_mask:0xf bank_mask:0xf
	v_cndmask_b32_dpp v213, v44, v45, vcc quad_perm:[1,0,3,2] row_mask:0xf bank_mask:0xf
	v_cndmask_b32_dpp v215, v46, v47, vcc quad_perm:[1,0,3,2] row_mask:0xf bank_mask:0xf
	s_waitcnt lgkmcnt(7)
	v_mfma_f32_16x16x32_bf16 v[16:19], v[136:139], v[80:83], v[16:19]
	s_mov_b64 vcc, s[20:21]
	v_cndmask_b32_dpp v220, v210, v208, vcc quad_perm:[2,3,0,1] row_mask:0xf bank_mask:0xf
	v_cndmask_b32_dpp v221, v211, v209, vcc quad_perm:[2,3,0,1] row_mask:0xf bank_mask:0xf
	v_cndmask_b32_dpp v224, v214, v212, vcc quad_perm:[2,3,0,1] row_mask:0xf bank_mask:0xf
	v_cndmask_b32_dpp v225, v215, v213, vcc quad_perm:[2,3,0,1] row_mask:0xf bank_mask:0xf
	s_waitcnt lgkmcnt(6)
	v_mfma_f32_16x16x32_bf16 v[16:19], v[140:143], v[84:87], v[16:19]
	s_mov_b64 vcc, s[22:23]
	v_cndmask_b32_dpp v222, v208, v210, vcc quad_perm:[2,3,0,1] row_mask:0xf bank_mask:0xf
	v_cndmask_b32_dpp v223, v209, v211, vcc quad_perm:[2,3,0,1] row_mask:0xf bank_mask:0xf
	v_cndmask_b32_dpp v226, v212, v214, vcc quad_perm:[2,3,0,1] row_mask:0xf bank_mask:0xf
	v_cndmask_b32_dpp v227, v213, v215, vcc quad_perm:[2,3,0,1] row_mask:0xf bank_mask:0xf
	s_nop 0
	global_store_dwordx4 v192, v[220:223], s[14:15] sc1
	global_store_dwordx4 v193, v[224:227], s[14:15] sc1
	s_waitcnt lgkmcnt(0)
	s_waitcnt vmcnt(4)
	s_barrier
	ds_read_b128 v[120:123], v93 offset:6144
	ds_read_b128 v[124:127], v93 offset:7168
	ds_read_b128 v[128:131], v93 offset:8192
	ds_read_b128 v[132:135], v93 offset:9216
	ds_read_b128 v[136:139], v93 offset:10240
	ds_read_b128 v[140:143], v93 offset:11264
	v_mfma_f32_16x16x32_bf16 v[20:23], v[96:99], v[80:83], v[20:23]
	ds_read_b128 v[96:99], v93
	v_mfma_f32_16x16x32_bf16 v[20:23], v[100:103], v[84:87], v[20:23]
	ds_read_b128 v[100:103], v93 offset:1024
	v_mfma_f32_16x16x32_bf16 v[28:31], v[104:107], v[80:83], v[28:31]
	ds_read_b128 v[104:107], v93 offset:2048
	v_mfma_f32_16x16x32_bf16 v[28:31], v[108:111], v[84:87], v[28:31]
	ds_read_b128 v[108:111], v93 offset:3072
	v_mfma_f32_16x16x32_bf16 v[24:27], v[112:115], v[80:83], v[24:27]
	ds_read_b128 v[112:115], v93 offset:4096
	v_mfma_f32_16x16x32_bf16 v[24:27], v[116:119], v[84:87], v[24:27]
	ds_read_b128 v[116:119], v93 offset:5120
	ds_read2st64_b64 v[172:175], v94 offset0:112 offset1:113
	ds_read2st64_b64 v[176:179], v94 offset0:114 offset1:115
	s_cmp_gt_u32 s3, 29
	s_cbranch_scc1 .Lscan_nodma
	s_add_i32 s0, s9, s6
	s_add_i32 m0, s0, 0x0
	s_nop 0
	global_load_lds_dwordx4 v48, s[10:11] nt
	s_add_i32 m0, s0, 0x2000
	s_nop 0
	global_load_lds_dwordx4 v181, s[10:11] nt
	s_add_i32 m0, s0, 0x4000
	s_nop 0
	global_load_lds_dwordx4 v182, s[10:11] nt
	s_add_i32 m0, s0, 0x6000
	s_nop 0
	global_load_lds_dwordx4 v183, s[10:11] nt
	s_add_i32 m0, s0, 0x8000
	s_nop 0
	global_load_lds_dwordx4 v184, s[10:11] nt
	s_add_i32 m0, s0, 0xa000
	s_nop 0
	global_load_lds_dwordx4 v185, s[10:11] nt
	s_add_i32 m0, s0, 0xc000
	s_nop 0
	global_load_lds_dwordx4 v186, s[10:11] nt
	s_add_i32 m0, s0, 0xe000
	s_nop 0
	global_load_lds_dwordx4 v48, s[12:13] nt
	s_add_i32 m0, s0, 0x10000
	s_nop 0
	global_load_lds_dwordx4 v181, s[12:13] nt
	s_add_u32 s10, s10, 0xe000
	s_addc_u32 s11, s11, 0
	s_add_u32 s12, s12, 0x4000
	s_addc_u32 s13, s13, 0
